# residual epilogue rewritten by hand: 16 loads first, packed f32 adds/squares, cvt_pk (on top of packed SwiGLU epilogue)
# baseline (speedup 1.0000x reference)
; __device__ __forceinline__ unsigned cvt_pk_bf16(float lo, float hi) { unsigned r; asm volatile("v_cvt_pk_bf16_f32 %0, %1, %2" : "=v"(r) : "v"(lo), "v"(hi)); return r; }
;     __device__ __forceinline__ void operator()(const f32x4 (&acc)[2][2][4][2], const Unit& u, int wr, int wc, int fr, int fq) const {
;     ...
;             for (int m = 0; m < 4; ++m) { const int row = row0 + ai * HALF + m * 16; const size_t off = (size_t)row * 1024 + col0; float part = 0.f;
; #pragma unroll
;                 for (int bj = 0; bj < 2; ++bj) { const u32x4 b = *(const u32x4*)(hb + off + bj * HALF);
;                     f32x4 v0 = acc[ai][bj][m][0], v1 = acc[ai][bj][m][1];
;                     v0[0] += __uint_as_float(b.x << 16); v0[1] += __uint_as_float(b.x & 0xffff0000u); v0[2] += __uint_as_float(b.y << 16); v0[3] += __uint_as_float(b.y & 0xffff0000u);
;                     v1[0] += __uint_as_float(b.z << 16); v1[1] += __uint_as_float(b.z & 0xffff0000u); v1[2] += __uint_as_float(b.w << 16); v1[3] += __uint_as_float(b.w & 0xffff0000u);
;                     u32x4 w; w.x = cvt_pk_bf16(v0[0], v0[1]); w.y = cvt_pk_bf16(v0[2], v0[3]); w.z = cvt_pk_bf16(v1[0], v1[1]); w.w = cvt_pk_bf16(v1[2], v1[3]);
;                     *(u32x4*)(hb + off + bj * HALF) = w;
;                     part += (v0[0] * v0[0] + v0[1] * v0[1]) + (v0[2] * v0[2] + v0[3] * v0[3]) + (v1[0] * v1[0] + v1[1] * v1[1]) + (v1[2] * v1[2] + v1[3] * v1[3]); }
.LBB0_641:
	v_lshl_add_u32 v246, s53, 8, v146
	v_lshl_or_b32 v247, s11, 8, v148
	v_lshlrev_b32_e32 v247, 1, v247
	v_lshl_add_u32 v142, v246, 11, v247
	v_add_u32_e32 v143, 0x8000, v142
	v_add_u32_e32 v144, 0x8000, v143
	v_add_u32_e32 v145, 0x8000, v144
	v_add_u32_e32 v204, 0x40000, v142
	v_add_u32_e32 v205, 0x40000, v143
	v_add_u32_e32 v206, 0x40000, v144
	v_add_u32_e32 v207, 0x40000, v145
	global_load_dwordx4 v[150:153], v142, s[8:9]
	global_load_dwordx4 v[154:157], v142, s[8:9] offset:256
	global_load_dwordx4 v[158:161], v143, s[8:9]
	global_load_dwordx4 v[162:165], v143, s[8:9] offset:256
	global_load_dwordx4 v[166:169], v144, s[8:9]
	global_load_dwordx4 v[170:173], v144, s[8:9] offset:256
	global_load_dwordx4 v[174:177], v145, s[8:9]
	global_load_dwordx4 v[178:181], v145, s[8:9] offset:256
	global_load_dwordx4 v[182:185], v204, s[8:9]
	global_load_dwordx4 v[186:189], v204, s[8:9] offset:256
	global_load_dwordx4 v[190:193], v205, s[8:9]
	global_load_dwordx4 v[194:197], v205, s[8:9] offset:256
	global_load_dwordx4 v[220:223], v206, s[8:9]
	global_load_dwordx4 v[224:227], v206, s[8:9] offset:256
	global_load_dwordx4 v[228:231], v207, s[8:9]
	global_load_dwordx4 v[232:235], v207, s[8:9] offset:256
	v_xor_b32_e32 v244, 16, v214
	v_lshlrev_b32_e32 v244, 2, v244
	v_xor_b32_e32 v245, 32, v214
	v_lshlrev_b32_e32 v245, 2, v245
	s_waitcnt vmcnt(14)
	v_lshlrev_b32_e32 v236, 16, v150
	v_and_b32_e32 v237, 0xffff0000, v150
	v_lshlrev_b32_e32 v238, 16, v151
	v_and_b32_e32 v239, 0xffff0000, v151
	v_lshlrev_b32_e32 v240, 16, v152
	v_and_b32_e32 v241, 0xffff0000, v152
	v_lshlrev_b32_e32 v242, 16, v153
	v_and_b32_e32 v243, 0xffff0000, v153
	v_pk_add_f32 v[128:129], v[128:129], v[236:237]
	v_pk_add_f32 v[130:131], v[130:131], v[238:239]
	v_pk_add_f32 v[124:125], v[124:125], v[240:241]
	v_pk_add_f32 v[126:127], v[126:127], v[242:243]
	v_cvt_pk_bf16_f32 v150, v128, v129
	v_cvt_pk_bf16_f32 v151, v130, v131
	v_cvt_pk_bf16_f32 v152, v124, v125
	v_cvt_pk_bf16_f32 v153, v126, v127
	global_store_dwordx4 v142, v[150:153], s[8:9]
	v_pk_mul_f32 v[248:249], v[128:129], v[128:129]
	v_pk_fma_f32 v[248:249], v[130:131], v[130:131], v[248:249]
	v_pk_fma_f32 v[248:249], v[124:125], v[124:125], v[248:249]
	v_pk_fma_f32 v[248:249], v[126:127], v[126:127], v[248:249]
	v_lshlrev_b32_e32 v236, 16, v154
	v_and_b32_e32 v237, 0xffff0000, v154
	v_lshlrev_b32_e32 v238, 16, v155
	v_and_b32_e32 v239, 0xffff0000, v155
	v_lshlrev_b32_e32 v240, 16, v156
	v_and_b32_e32 v241, 0xffff0000, v156
	v_lshlrev_b32_e32 v242, 16, v157
	v_and_b32_e32 v243, 0xffff0000, v157
	v_pk_add_f32 v[120:121], v[120:121], v[236:237]
	v_pk_add_f32 v[122:123], v[122:123], v[238:239]
	v_pk_add_f32 v[116:117], v[116:117], v[240:241]
	v_pk_add_f32 v[118:119], v[118:119], v[242:243]
	v_cvt_pk_bf16_f32 v154, v120, v121
	v_cvt_pk_bf16_f32 v155, v122, v123
	v_cvt_pk_bf16_f32 v156, v116, v117
	v_cvt_pk_bf16_f32 v157, v118, v119
	global_store_dwordx4 v142, v[154:157], s[8:9] offset:256
	v_pk_fma_f32 v[248:249], v[120:121], v[120:121], v[248:249]
	v_pk_fma_f32 v[248:249], v[122:123], v[122:123], v[248:249]
	v_pk_fma_f32 v[248:249], v[116:117], v[116:117], v[248:249]
	v_pk_fma_f32 v[248:249], v[118:119], v[118:119], v[248:249]
	v_add_f32_e32 v128, v248, v249
	s_waitcnt vmcnt(14)
	v_lshlrev_b32_e32 v236, 16, v158
	v_and_b32_e32 v237, 0xffff0000, v158
	v_lshlrev_b32_e32 v238, 16, v159
	v_and_b32_e32 v239, 0xffff0000, v159
	v_lshlrev_b32_e32 v240, 16, v160
	v_and_b32_e32 v241, 0xffff0000, v160
	v_lshlrev_b32_e32 v242, 16, v161
	v_and_b32_e32 v243, 0xffff0000, v161
	v_pk_add_f32 v[112:113], v[112:113], v[236:237]
	v_pk_add_f32 v[114:115], v[114:115], v[238:239]
	v_pk_add_f32 v[108:109], v[108:109], v[240:241]
	v_pk_add_f32 v[110:111], v[110:111], v[242:243]
	v_cvt_pk_bf16_f32 v158, v112, v113
	v_cvt_pk_bf16_f32 v159, v114, v115
	v_cvt_pk_bf16_f32 v160, v108, v109
	v_cvt_pk_bf16_f32 v161, v110, v111
	global_store_dwordx4 v143, v[158:161], s[8:9]
	v_pk_mul_f32 v[248:249], v[112:113], v[112:113]
	v_pk_fma_f32 v[248:249], v[114:115], v[114:115], v[248:249]
	v_pk_fma_f32 v[248:249], v[108:109], v[108:109], v[248:249]
	v_pk_fma_f32 v[248:249], v[110:111], v[110:111], v[248:249]
	v_lshlrev_b32_e32 v236, 16, v162
	v_and_b32_e32 v237, 0xffff0000, v162
	v_lshlrev_b32_e32 v238, 16, v163
	v_and_b32_e32 v239, 0xffff0000, v163
	v_lshlrev_b32_e32 v240, 16, v164
	v_and_b32_e32 v241, 0xffff0000, v164
	v_lshlrev_b32_e32 v242, 16, v165
	v_and_b32_e32 v243, 0xffff0000, v165
	v_pk_add_f32 v[104:105], v[104:105], v[236:237]
	v_pk_add_f32 v[106:107], v[106:107], v[238:239]
	v_pk_add_f32 v[100:101], v[100:101], v[240:241]
	v_pk_add_f32 v[102:103], v[102:103], v[242:243]
	v_cvt_pk_bf16_f32 v162, v104, v105
	v_cvt_pk_bf16_f32 v163, v106, v107
	v_cvt_pk_bf16_f32 v164, v100, v101
	v_cvt_pk_bf16_f32 v165, v102, v103
	global_store_dwordx4 v143, v[162:165], s[8:9] offset:256
	v_pk_fma_f32 v[248:249], v[104:105], v[104:105], v[248:249]
	v_pk_fma_f32 v[248:249], v[106:107], v[106:107], v[248:249]
	v_pk_fma_f32 v[248:249], v[100:101], v[100:101], v[248:249]
	v_pk_fma_f32 v[248:249], v[102:103], v[102:103], v[248:249]
	v_add_f32_e32 v112, v248, v249
	s_waitcnt vmcnt(14)
; __device__ __forceinline__ unsigned cvt_pk_bf16(float lo, float hi) { unsigned r; asm volatile("v_cvt_pk_bf16_f32 %0, %1, %2" : "=v"(r) : "v"(lo), "v"(hi)); return r; }
;     __device__ __forceinline__ void operator()(const f32x4 (&acc)[2][2][4][2], const Unit& u, int wr, int wc, int fr, int fq) const {
;     ...
;             for (int m = 0; m < 4; ++m) { const int row = row0 + ai * HALF + m * 16; const size_t off = (size_t)row * 1024 + col0; float part = 0.f;
; #pragma unroll
;                 for (int bj = 0; bj < 2; ++bj) { const u32x4 b = *(const u32x4*)(hb + off + bj * HALF);
;                     f32x4 v0 = acc[ai][bj][m][0], v1 = acc[ai][bj][m][1];
;                     v0[0] += __uint_as_float(b.x << 16); v0[1] += __uint_as_float(b.x & 0xffff0000u); v0[2] += __uint_as_float(b.y << 16); v0[3] += __uint_as_float(b.y & 0xffff0000u);
;                     v1[0] += __uint_as_float(b.z << 16); v1[1] += __uint_as_float(b.z & 0xffff0000u); v1[2] += __uint_as_float(b.w << 16); v1[3] += __uint_as_float(b.w & 0xffff0000u);
;                     u32x4 w; w.x = cvt_pk_bf16(v0[0], v0[1]); w.y = cvt_pk_bf16(v0[2], v0[3]); w.z = cvt_pk_bf16(v1[0], v1[1]); w.w = cvt_pk_bf16(v1[2], v1[3]);
;                     *(u32x4*)(hb + off + bj * HALF) = w;
;                     part += (v0[0] * v0[0] + v0[1] * v0[1]) + (v0[2] * v0[2] + v0[3] * v0[3]) + (v1[0] * v1[0] + v1[1] * v1[1]) + (v1[2] * v1[2] + v1[3] * v1[3]); }
	v_lshlrev_b32_e32 v236, 16, v166
	v_and_b32_e32 v237, 0xffff0000, v166
	v_lshlrev_b32_e32 v238, 16, v167
	v_and_b32_e32 v239, 0xffff0000, v167
	v_lshlrev_b32_e32 v240, 16, v168
	v_and_b32_e32 v241, 0xffff0000, v168
	v_lshlrev_b32_e32 v242, 16, v169
	v_and_b32_e32 v243, 0xffff0000, v169
	v_pk_add_f32 v[96:97], v[96:97], v[236:237]
	v_pk_add_f32 v[98:99], v[98:99], v[238:239]
	v_pk_add_f32 v[92:93], v[92:93], v[240:241]
	v_pk_add_f32 v[94:95], v[94:95], v[242:243]
	v_cvt_pk_bf16_f32 v166, v96, v97
	v_cvt_pk_bf16_f32 v167, v98, v99
	v_cvt_pk_bf16_f32 v168, v92, v93
	v_cvt_pk_bf16_f32 v169, v94, v95
	global_store_dwordx4 v144, v[166:169], s[8:9]
	v_pk_mul_f32 v[248:249], v[96:97], v[96:97]
	v_pk_fma_f32 v[248:249], v[98:99], v[98:99], v[248:249]
	v_pk_fma_f32 v[248:249], v[92:93], v[92:93], v[248:249]
	v_pk_fma_f32 v[248:249], v[94:95], v[94:95], v[248:249]
	v_lshlrev_b32_e32 v236, 16, v170
	v_and_b32_e32 v237, 0xffff0000, v170
	v_lshlrev_b32_e32 v238, 16, v171
	v_and_b32_e32 v239, 0xffff0000, v171
	v_lshlrev_b32_e32 v240, 16, v172
	v_and_b32_e32 v241, 0xffff0000, v172
	v_lshlrev_b32_e32 v242, 16, v173
	v_and_b32_e32 v243, 0xffff0000, v173
	v_pk_add_f32 v[88:89], v[88:89], v[236:237]
	v_pk_add_f32 v[90:91], v[90:91], v[238:239]
	v_pk_add_f32 v[84:85], v[84:85], v[240:241]
	v_pk_add_f32 v[86:87], v[86:87], v[242:243]
	v_cvt_pk_bf16_f32 v170, v88, v89
	v_cvt_pk_bf16_f32 v171, v90, v91
	v_cvt_pk_bf16_f32 v172, v84, v85
	v_cvt_pk_bf16_f32 v173, v86, v87
	global_store_dwordx4 v144, v[170:173], s[8:9] offset:256
	v_pk_fma_f32 v[248:249], v[88:89], v[88:89], v[248:249]
	v_pk_fma_f32 v[248:249], v[90:91], v[90:91], v[248:249]
	v_pk_fma_f32 v[248:249], v[84:85], v[84:85], v[248:249]
	v_pk_fma_f32 v[248:249], v[86:87], v[86:87], v[248:249]
	v_add_f32_e32 v96, v248, v249
	s_waitcnt vmcnt(14)
	v_lshlrev_b32_e32 v236, 16, v174
	v_and_b32_e32 v237, 0xffff0000, v174
	v_lshlrev_b32_e32 v238, 16, v175
	v_and_b32_e32 v239, 0xffff0000, v175
	v_lshlrev_b32_e32 v240, 16, v176
	v_and_b32_e32 v241, 0xffff0000, v176
	v_lshlrev_b32_e32 v242, 16, v177
	v_and_b32_e32 v243, 0xffff0000, v177
	v_pk_add_f32 v[80:81], v[80:81], v[236:237]
	v_pk_add_f32 v[82:83], v[82:83], v[238:239]
	v_pk_add_f32 v[76:77], v[76:77], v[240:241]
	v_pk_add_f32 v[78:79], v[78:79], v[242:243]
	v_cvt_pk_bf16_f32 v174, v80, v81
	v_cvt_pk_bf16_f32 v175, v82, v83
	v_cvt_pk_bf16_f32 v176, v76, v77
	v_cvt_pk_bf16_f32 v177, v78, v79
	global_store_dwordx4 v145, v[174:177], s[8:9]
	v_pk_mul_f32 v[248:249], v[80:81], v[80:81]
	v_pk_fma_f32 v[248:249], v[82:83], v[82:83], v[248:249]
	v_pk_fma_f32 v[248:249], v[76:77], v[76:77], v[248:249]
	v_pk_fma_f32 v[248:249], v[78:79], v[78:79], v[248:249]
	v_lshlrev_b32_e32 v236, 16, v178
	v_and_b32_e32 v237, 0xffff0000, v178
	v_lshlrev_b32_e32 v238, 16, v179
	v_and_b32_e32 v239, 0xffff0000, v179
	v_lshlrev_b32_e32 v240, 16, v180
	v_and_b32_e32 v241, 0xffff0000, v180
	v_lshlrev_b32_e32 v242, 16, v181
	v_and_b32_e32 v243, 0xffff0000, v181
	v_pk_add_f32 v[72:73], v[72:73], v[236:237]
	v_pk_add_f32 v[74:75], v[74:75], v[238:239]
	v_pk_add_f32 v[68:69], v[68:69], v[240:241]
	v_pk_add_f32 v[70:71], v[70:71], v[242:243]
	v_cvt_pk_bf16_f32 v178, v72, v73
	v_cvt_pk_bf16_f32 v179, v74, v75
	v_cvt_pk_bf16_f32 v180, v68, v69
	v_cvt_pk_bf16_f32 v181, v70, v71
	global_store_dwordx4 v145, v[178:181], s[8:9] offset:256
	v_pk_fma_f32 v[248:249], v[72:73], v[72:73], v[248:249]
	v_pk_fma_f32 v[248:249], v[74:75], v[74:75], v[248:249]
	v_pk_fma_f32 v[248:249], v[68:69], v[68:69], v[248:249]
	v_pk_fma_f32 v[248:249], v[70:71], v[70:71], v[248:249]
	v_add_f32_e32 v80, v248, v249
	s_waitcnt vmcnt(14)
	v_lshlrev_b32_e32 v236, 16, v182
	v_and_b32_e32 v237, 0xffff0000, v182
	v_lshlrev_b32_e32 v238, 16, v183
	v_and_b32_e32 v239, 0xffff0000, v183
	v_lshlrev_b32_e32 v240, 16, v184
	v_and_b32_e32 v241, 0xffff0000, v184
	v_lshlrev_b32_e32 v242, 16, v185
	v_and_b32_e32 v243, 0xffff0000, v185
	v_pk_add_f32 v[64:65], v[64:65], v[236:237]
	v_pk_add_f32 v[66:67], v[66:67], v[238:239]
	v_pk_add_f32 v[60:61], v[60:61], v[240:241]
	v_pk_add_f32 v[62:63], v[62:63], v[242:243]
	v_cvt_pk_bf16_f32 v182, v64, v65
	v_cvt_pk_bf16_f32 v183, v66, v67
	v_cvt_pk_bf16_f32 v184, v60, v61
	v_cvt_pk_bf16_f32 v185, v62, v63
	global_store_dwordx4 v204, v[182:185], s[8:9]
	v_pk_mul_f32 v[248:249], v[64:65], v[64:65]
	v_pk_fma_f32 v[248:249], v[66:67], v[66:67], v[248:249]
	v_pk_fma_f32 v[248:249], v[60:61], v[60:61], v[248:249]
	v_pk_fma_f32 v[248:249], v[62:63], v[62:63], v[248:249]
	v_lshlrev_b32_e32 v236, 16, v186
	v_and_b32_e32 v237, 0xffff0000, v186
	v_lshlrev_b32_e32 v238, 16, v187
	v_and_b32_e32 v239, 0xffff0000, v187
	v_lshlrev_b32_e32 v240, 16, v188
	v_and_b32_e32 v241, 0xffff0000, v188
	v_lshlrev_b32_e32 v242, 16, v189
	v_and_b32_e32 v243, 0xffff0000, v189
	v_pk_add_f32 v[56:57], v[56:57], v[236:237]
	v_pk_add_f32 v[58:59], v[58:59], v[238:239]
	v_pk_add_f32 v[52:53], v[52:53], v[240:241]
	v_pk_add_f32 v[54:55], v[54:55], v[242:243]
	v_cvt_pk_bf16_f32 v186, v56, v57
	v_cvt_pk_bf16_f32 v187, v58, v59
	v_cvt_pk_bf16_f32 v188, v52, v53
	v_cvt_pk_bf16_f32 v189, v54, v55
	global_store_dwordx4 v204, v[186:189], s[8:9] offset:256
	v_pk_fma_f32 v[248:249], v[56:57], v[56:57], v[248:249]
	v_pk_fma_f32 v[248:249], v[58:59], v[58:59], v[248:249]
	v_pk_fma_f32 v[248:249], v[52:53], v[52:53], v[248:249]
	v_pk_fma_f32 v[248:249], v[54:55], v[54:55], v[248:249]
	v_add_f32_e32 v64, v248, v249
	s_waitcnt vmcnt(14)
; __device__ __forceinline__ unsigned cvt_pk_bf16(float lo, float hi) { unsigned r; asm volatile("v_cvt_pk_bf16_f32 %0, %1, %2" : "=v"(r) : "v"(lo), "v"(hi)); return r; }
;     __device__ __forceinline__ void operator()(const f32x4 (&acc)[2][2][4][2], const Unit& u, int wr, int wc, int fr, int fq) const {
;     ...
;             for (int m = 0; m < 4; ++m) { const int row = row0 + ai * HALF + m * 16; const size_t off = (size_t)row * 1024 + col0; float part = 0.f;
; #pragma unroll
;                 for (int bj = 0; bj < 2; ++bj) { const u32x4 b = *(const u32x4*)(hb + off + bj * HALF);
;                     f32x4 v0 = acc[ai][bj][m][0], v1 = acc[ai][bj][m][1];
;                     v0[0] += __uint_as_float(b.x << 16); v0[1] += __uint_as_float(b.x & 0xffff0000u); v0[2] += __uint_as_float(b.y << 16); v0[3] += __uint_as_float(b.y & 0xffff0000u);
;                     v1[0] += __uint_as_float(b.z << 16); v1[1] += __uint_as_float(b.z & 0xffff0000u); v1[2] += __uint_as_float(b.w << 16); v1[3] += __uint_as_float(b.w & 0xffff0000u);
;                     u32x4 w; w.x = cvt_pk_bf16(v0[0], v0[1]); w.y = cvt_pk_bf16(v0[2], v0[3]); w.z = cvt_pk_bf16(v1[0], v1[1]); w.w = cvt_pk_bf16(v1[2], v1[3]);
;                     *(u32x4*)(hb + off + bj * HALF) = w;
;                     part += (v0[0] * v0[0] + v0[1] * v0[1]) + (v0[2] * v0[2] + v0[3] * v0[3]) + (v1[0] * v1[0] + v1[1] * v1[1]) + (v1[2] * v1[2] + v1[3] * v1[3]); }
	v_lshlrev_b32_e32 v236, 16, v190
	v_and_b32_e32 v237, 0xffff0000, v190
	v_lshlrev_b32_e32 v238, 16, v191
	v_and_b32_e32 v239, 0xffff0000, v191
	v_lshlrev_b32_e32 v240, 16, v192
	v_and_b32_e32 v241, 0xffff0000, v192
	v_lshlrev_b32_e32 v242, 16, v193
	v_and_b32_e32 v243, 0xffff0000, v193
	v_pk_add_f32 v[48:49], v[48:49], v[236:237]
	v_pk_add_f32 v[50:51], v[50:51], v[238:239]
	v_pk_add_f32 v[44:45], v[44:45], v[240:241]
	v_pk_add_f32 v[46:47], v[46:47], v[242:243]
	v_cvt_pk_bf16_f32 v190, v48, v49
	v_cvt_pk_bf16_f32 v191, v50, v51
	v_cvt_pk_bf16_f32 v192, v44, v45
	v_cvt_pk_bf16_f32 v193, v46, v47
	global_store_dwordx4 v205, v[190:193], s[8:9]
	v_pk_mul_f32 v[248:249], v[48:49], v[48:49]
	v_pk_fma_f32 v[248:249], v[50:51], v[50:51], v[248:249]
	v_pk_fma_f32 v[248:249], v[44:45], v[44:45], v[248:249]
	v_pk_fma_f32 v[248:249], v[46:47], v[46:47], v[248:249]
	v_lshlrev_b32_e32 v236, 16, v194
	v_and_b32_e32 v237, 0xffff0000, v194
	v_lshlrev_b32_e32 v238, 16, v195
	v_and_b32_e32 v239, 0xffff0000, v195
	v_lshlrev_b32_e32 v240, 16, v196
	v_and_b32_e32 v241, 0xffff0000, v196
	v_lshlrev_b32_e32 v242, 16, v197
	v_and_b32_e32 v243, 0xffff0000, v197
	v_pk_add_f32 v[40:41], v[40:41], v[236:237]
	v_pk_add_f32 v[42:43], v[42:43], v[238:239]
	v_pk_add_f32 v[36:37], v[36:37], v[240:241]
	v_pk_add_f32 v[38:39], v[38:39], v[242:243]
	v_cvt_pk_bf16_f32 v194, v40, v41
	v_cvt_pk_bf16_f32 v195, v42, v43
	v_cvt_pk_bf16_f32 v196, v36, v37
	v_cvt_pk_bf16_f32 v197, v38, v39
	global_store_dwordx4 v205, v[194:197], s[8:9] offset:256
	v_pk_fma_f32 v[248:249], v[40:41], v[40:41], v[248:249]
	v_pk_fma_f32 v[248:249], v[42:43], v[42:43], v[248:249]
	v_pk_fma_f32 v[248:249], v[36:37], v[36:37], v[248:249]
	v_pk_fma_f32 v[248:249], v[38:39], v[38:39], v[248:249]
	v_add_f32_e32 v48, v248, v249
	s_waitcnt vmcnt(14)
	v_lshlrev_b32_e32 v236, 16, v220
	v_and_b32_e32 v237, 0xffff0000, v220
	v_lshlrev_b32_e32 v238, 16, v221
	v_and_b32_e32 v239, 0xffff0000, v221
	v_lshlrev_b32_e32 v240, 16, v222
	v_and_b32_e32 v241, 0xffff0000, v222
	v_lshlrev_b32_e32 v242, 16, v223
	v_and_b32_e32 v243, 0xffff0000, v223
	v_pk_add_f32 v[32:33], v[32:33], v[236:237]
	v_pk_add_f32 v[34:35], v[34:35], v[238:239]
	v_pk_add_f32 v[28:29], v[28:29], v[240:241]
	v_pk_add_f32 v[30:31], v[30:31], v[242:243]
	v_cvt_pk_bf16_f32 v220, v32, v33
	v_cvt_pk_bf16_f32 v221, v34, v35
	v_cvt_pk_bf16_f32 v222, v28, v29
	v_cvt_pk_bf16_f32 v223, v30, v31
	global_store_dwordx4 v206, v[220:223], s[8:9]
	v_pk_mul_f32 v[248:249], v[32:33], v[32:33]
	v_pk_fma_f32 v[248:249], v[34:35], v[34:35], v[248:249]
	v_pk_fma_f32 v[248:249], v[28:29], v[28:29], v[248:249]
	v_pk_fma_f32 v[248:249], v[30:31], v[30:31], v[248:249]
	v_lshlrev_b32_e32 v236, 16, v224
	v_and_b32_e32 v237, 0xffff0000, v224
	v_lshlrev_b32_e32 v238, 16, v225
	v_and_b32_e32 v239, 0xffff0000, v225
	v_lshlrev_b32_e32 v240, 16, v226
	v_and_b32_e32 v241, 0xffff0000, v226
	v_lshlrev_b32_e32 v242, 16, v227
	v_and_b32_e32 v243, 0xffff0000, v227
	v_pk_add_f32 v[24:25], v[24:25], v[236:237]
	v_pk_add_f32 v[26:27], v[26:27], v[238:239]
	v_pk_add_f32 v[20:21], v[20:21], v[240:241]
	v_pk_add_f32 v[22:23], v[22:23], v[242:243]
	v_cvt_pk_bf16_f32 v224, v24, v25
	v_cvt_pk_bf16_f32 v225, v26, v27
	v_cvt_pk_bf16_f32 v226, v20, v21
	v_cvt_pk_bf16_f32 v227, v22, v23
	global_store_dwordx4 v206, v[224:227], s[8:9] offset:256
	v_pk_fma_f32 v[248:249], v[24:25], v[24:25], v[248:249]
	v_pk_fma_f32 v[248:249], v[26:27], v[26:27], v[248:249]
	v_pk_fma_f32 v[248:249], v[20:21], v[20:21], v[248:249]
	v_pk_fma_f32 v[248:249], v[22:23], v[22:23], v[248:249]
	v_add_f32_e32 v32, v248, v249
	s_waitcnt vmcnt(14)
; __device__ __forceinline__ unsigned cvt_pk_bf16(float lo, float hi) { unsigned r; asm volatile("v_cvt_pk_bf16_f32 %0, %1, %2" : "=v"(r) : "v"(lo), "v"(hi)); return r; }
;     __device__ __forceinline__ void operator()(const f32x4 (&acc)[2][2][4][2], const Unit& u, int wr, int wc, int fr, int fq) const {
;     ...
;             for (int m = 0; m < 4; ++m) { const int row = row0 + ai * HALF + m * 16; const size_t off = (size_t)row * 1024 + col0; float part = 0.f;
; #pragma unroll
;                 for (int bj = 0; bj < 2; ++bj) { const u32x4 b = *(const u32x4*)(hb + off + bj * HALF);
;                     f32x4 v0 = acc[ai][bj][m][0], v1 = acc[ai][bj][m][1];
;                     v0[0] += __uint_as_float(b.x << 16); v0[1] += __uint_as_float(b.x & 0xffff0000u); v0[2] += __uint_as_float(b.y << 16); v0[3] += __uint_as_float(b.y & 0xffff0000u);
;                     v1[0] += __uint_as_float(b.z << 16); v1[1] += __uint_as_float(b.z & 0xffff0000u); v1[2] += __uint_as_float(b.w << 16); v1[3] += __uint_as_float(b.w & 0xffff0000u);
;                     u32x4 w; w.x = cvt_pk_bf16(v0[0], v0[1]); w.y = cvt_pk_bf16(v0[2], v0[3]); w.z = cvt_pk_bf16(v1[0], v1[1]); w.w = cvt_pk_bf16(v1[2], v1[3]);
;                     *(u32x4*)(hb + off + bj * HALF) = w;
;                     part += (v0[0] * v0[0] + v0[1] * v0[1]) + (v0[2] * v0[2] + v0[3] * v0[3]) + (v1[0] * v1[0] + v1[1] * v1[1]) + (v1[2] * v1[2] + v1[3] * v1[3]); }
;                 part += __shfl_xor(part, 16); part += __shfl_xor(part, 32);
;                 if (fq == 0) ssq[(size_t)row * 16 + u.pn * 4 + wc] = part; }
	v_lshlrev_b32_e32 v236, 16, v228
	v_and_b32_e32 v237, 0xffff0000, v228
	v_lshlrev_b32_e32 v238, 16, v229
	v_and_b32_e32 v239, 0xffff0000, v229
	v_lshlrev_b32_e32 v240, 16, v230
	v_and_b32_e32 v241, 0xffff0000, v230
	v_lshlrev_b32_e32 v242, 16, v231
	v_and_b32_e32 v243, 0xffff0000, v231
	v_pk_add_f32 v[16:17], v[16:17], v[236:237]
	v_pk_add_f32 v[18:19], v[18:19], v[238:239]
	v_pk_add_f32 v[12:13], v[12:13], v[240:241]
	v_pk_add_f32 v[14:15], v[14:15], v[242:243]
	v_cvt_pk_bf16_f32 v228, v16, v17
	v_cvt_pk_bf16_f32 v229, v18, v19
	v_cvt_pk_bf16_f32 v230, v12, v13
	v_cvt_pk_bf16_f32 v231, v14, v15
	global_store_dwordx4 v207, v[228:231], s[8:9]
	v_pk_mul_f32 v[248:249], v[16:17], v[16:17]
	v_pk_fma_f32 v[248:249], v[18:19], v[18:19], v[248:249]
	v_pk_fma_f32 v[248:249], v[12:13], v[12:13], v[248:249]
	v_pk_fma_f32 v[248:249], v[14:15], v[14:15], v[248:249]
	v_lshlrev_b32_e32 v236, 16, v232
	v_and_b32_e32 v237, 0xffff0000, v232
	v_lshlrev_b32_e32 v238, 16, v233
	v_and_b32_e32 v239, 0xffff0000, v233
	v_lshlrev_b32_e32 v240, 16, v234
	v_and_b32_e32 v241, 0xffff0000, v234
	v_lshlrev_b32_e32 v242, 16, v235
	v_and_b32_e32 v243, 0xffff0000, v235
	v_pk_add_f32 v[8:9], v[8:9], v[236:237]
	v_pk_add_f32 v[10:11], v[10:11], v[238:239]
	v_pk_add_f32 v[4:5], v[4:5], v[240:241]
	v_pk_add_f32 v[6:7], v[6:7], v[242:243]
	v_cvt_pk_bf16_f32 v232, v8, v9
	v_cvt_pk_bf16_f32 v233, v10, v11
	v_cvt_pk_bf16_f32 v234, v4, v5
	v_cvt_pk_bf16_f32 v235, v6, v7
	global_store_dwordx4 v207, v[232:235], s[8:9] offset:256
	v_pk_fma_f32 v[248:249], v[8:9], v[8:9], v[248:249]
	v_pk_fma_f32 v[248:249], v[10:11], v[10:11], v[248:249]
	v_pk_fma_f32 v[248:249], v[4:5], v[4:5], v[248:249]
	v_pk_fma_f32 v[248:249], v[6:7], v[6:7], v[248:249]
	v_add_f32_e32 v16, v248, v249
	ds_bpermute_b32 v129, v244, v128
	ds_bpermute_b32 v113, v244, v112
	ds_bpermute_b32 v97, v244, v96
	ds_bpermute_b32 v81, v244, v80
	ds_bpermute_b32 v65, v244, v64
	ds_bpermute_b32 v49, v244, v48
	ds_bpermute_b32 v33, v244, v32
	ds_bpermute_b32 v17, v244, v16
	s_waitcnt lgkmcnt(7)
	v_add_f32_e32 v128, v128, v129
	s_waitcnt lgkmcnt(6)
	v_add_f32_e32 v112, v112, v113
	s_waitcnt lgkmcnt(5)
	v_add_f32_e32 v96, v96, v97
	s_waitcnt lgkmcnt(4)
	v_add_f32_e32 v80, v80, v81
	s_waitcnt lgkmcnt(3)
	v_add_f32_e32 v64, v64, v65
	s_waitcnt lgkmcnt(2)
	v_add_f32_e32 v48, v48, v49
	s_waitcnt lgkmcnt(1)
	v_add_f32_e32 v32, v32, v33
	s_waitcnt lgkmcnt(0)
	v_add_f32_e32 v16, v16, v17
	ds_bpermute_b32 v129, v245, v128
	ds_bpermute_b32 v113, v245, v112
	ds_bpermute_b32 v97, v245, v96
	ds_bpermute_b32 v81, v245, v80
	ds_bpermute_b32 v65, v245, v64
	ds_bpermute_b32 v49, v245, v48
	ds_bpermute_b32 v33, v245, v32
	ds_bpermute_b32 v17, v245, v16
	s_waitcnt lgkmcnt(7)
	v_add_f32_e32 v128, v128, v129
	s_waitcnt lgkmcnt(6)
	v_add_f32_e32 v112, v112, v113
	s_waitcnt lgkmcnt(5)
	v_add_f32_e32 v96, v96, v97
	s_waitcnt lgkmcnt(4)
	v_add_f32_e32 v80, v80, v81
	s_waitcnt lgkmcnt(3)
	v_add_f32_e32 v64, v64, v65
	s_waitcnt lgkmcnt(2)
	v_add_f32_e32 v48, v48, v49
	s_waitcnt lgkmcnt(1)
	v_add_f32_e32 v32, v32, v33
	s_waitcnt lgkmcnt(0)
	v_add_f32_e32 v16, v16, v17
	s_lshl_b32 s28, s11, 4
	s_lshl_b32 s84, s43, 2
	s_add_i32 s28, s28, s84
	v_lshl_add_u32 v247, v246, 6, s28
	s_and_saveexec_b64 s[26:27], s[2:3]
	global_store_dword v247, v128, s[20:21]
	global_store_dword v247, v112, s[20:21] offset:1024
	global_store_dword v247, v96, s[20:21] offset:2048
	global_store_dword v247, v80, s[20:21] offset:3072
	v_add_u32_e32 v247, 0x2000, v247
	global_store_dword v247, v64, s[20:21]
	global_store_dword v247, v48, s[20:21] offset:1024
	global_store_dword v247, v32, s[20:21] offset:2048
	global_store_dword v247, v16, s[20:21] offset:3072
	s_or_b64 exec, exec, s[26:27]
	s_lshl_b32 s28, s11, 2
	s_ashr_i32 s29, s28, 31
	s_and_b64 vcc, exec, s[4:5]
	s_mov_b64 s[4:5], -1
	s_cbranch_vccnz .LBB0_626
	s_andn2_b64 vcc, exec, s[18:19]
	s_cbranch_vccnz .LBB0_625
	s_barrier
	s_branch .LBB0_625
